# GEMM accumulator clears with 64-bit moves (half the instructions)
# speedup vs baseline: 1.0056x; 1.0044x over previous
.LBB0_377:
	s_ashr_i32 s55, s54, 31
	s_lshl_b64 s[8:9], s[54:55], 19
	v_readlane_b32 s10, v251, 3
	v_readlane_b32 s11, v251, 4
	s_add_u32 s56, s10, s8
	s_addc_u32 s57, s11, s9
	s_ashr_i32 s53, s52, 31
	s_lshl_b64 s[8:9], s[52:53], 19
	v_mov_b64_e32 v[0:1], 0x4a4
	s_add_u32 s58, s5, s8
	v_mov_b32_e32 v127, 0
	v_cmp_lt_i64_e64 s[0:1], s[0:1], v[0:1]
	s_addc_u32 s59, s6, s9
	s_andn2_b64 vcc, exec, s[50:51]
	v_mov_b32_e32 v126, v127
	v_mov_b64_e32 v[124:125], 0
	v_mov_b64_e32 v[122:123], 0
	v_mov_b64_e32 v[120:121], 0
	v_mov_b64_e32 v[110:111], 0
	v_mov_b64_e32 v[108:109], 0
	v_mov_b64_e32 v[106:107], 0
	v_mov_b64_e32 v[104:105], 0
	v_mov_b64_e32 v[94:95], 0
	v_mov_b64_e32 v[92:93], 0
	v_mov_b64_e32 v[90:91], 0
	v_mov_b64_e32 v[88:89], 0
	v_mov_b64_e32 v[78:79], 0
	v_mov_b64_e32 v[76:77], 0
	v_mov_b64_e32 v[74:75], 0
	v_mov_b64_e32 v[72:73], 0
	v_mov_b64_e32 v[118:119], 0
	v_mov_b64_e32 v[116:117], 0
	v_mov_b64_e32 v[114:115], 0
	v_mov_b64_e32 v[112:113], 0
	v_mov_b64_e32 v[102:103], 0
	v_mov_b64_e32 v[100:101], 0
	v_mov_b64_e32 v[98:99], 0
	v_mov_b64_e32 v[96:97], 0
	v_mov_b64_e32 v[86:87], 0
	v_mov_b64_e32 v[84:85], 0
	v_mov_b64_e32 v[82:83], 0
	v_mov_b64_e32 v[80:81], 0
	v_mov_b64_e32 v[70:71], 0
	v_mov_b64_e32 v[68:69], 0
	v_mov_b64_e32 v[66:67], 0
	v_mov_b64_e32 v[64:65], 0
	v_mov_b64_e32 v[62:63], 0
	v_mov_b64_e32 v[60:61], 0
	v_mov_b64_e32 v[58:59], 0
	v_mov_b64_e32 v[56:57], 0
	v_mov_b64_e32 v[46:47], 0
	v_mov_b64_e32 v[44:45], 0
	v_mov_b64_e32 v[42:43], 0
	v_mov_b64_e32 v[40:41], 0
	v_mov_b64_e32 v[30:31], 0
	v_mov_b64_e32 v[28:29], 0
	v_mov_b64_e32 v[26:27], 0
	v_mov_b64_e32 v[24:25], 0
	v_mov_b64_e32 v[14:15], 0
	v_mov_b64_e32 v[12:13], 0
	v_mov_b64_e32 v[10:11], 0
	v_mov_b64_e32 v[8:9], 0
	v_mov_b64_e32 v[54:55], 0
	v_mov_b64_e32 v[52:53], 0
	v_mov_b64_e32 v[50:51], 0
	v_mov_b64_e32 v[48:49], 0
	v_mov_b64_e32 v[38:39], 0
	v_mov_b64_e32 v[36:37], 0
	v_mov_b64_e32 v[34:35], 0
	v_mov_b64_e32 v[32:33], 0
	v_mov_b64_e32 v[22:23], 0
	v_mov_b64_e32 v[20:21], 0
	v_mov_b64_e32 v[18:19], 0
	v_mov_b64_e32 v[16:17], 0
	v_mov_b64_e32 v[6:7], 0
	v_mov_b64_e32 v[4:5], 0
	v_mov_b64_e32 v[2:3], 0
	v_mov_b64_e32 v[0:1], 0
	s_cbranch_vccnz .LBB0_381
	s_and_b64 s[0:1], s[0:1], exec
	s_cselect_b32 s8, s57, s49
	s_cselect_b32 s9, s56, s48
	s_cselect_b32 s19, s59, s47
	s_cselect_b32 s45, s58, s46
	s_add_u32 s53, s46, 0x100
	s_addc_u32 s55, s47, 0
	s_add_u32 s0, s48, 0x40080
	v_mov_b32_e32 v0, 0
	s_addc_u32 s1, s49, 0
	s_mov_b32 s46, 0
	v_mov_b32_e32 v1, v0
	v_mov_b64_e32 v[2:3], 0
	v_mov_b64_e32 v[4:5], 0
	v_mov_b64_e32 v[6:7], 0
	v_mov_b64_e32 v[16:17], 0
	v_mov_b64_e32 v[18:19], 0
	v_mov_b64_e32 v[20:21], 0
	v_mov_b64_e32 v[22:23], 0
	v_mov_b64_e32 v[32:33], 0
	v_mov_b64_e32 v[34:35], 0
	v_mov_b64_e32 v[36:37], 0
	v_mov_b64_e32 v[38:39], 0
	v_mov_b64_e32 v[48:49], 0
	v_mov_b64_e32 v[50:51], 0
	v_mov_b64_e32 v[52:53], 0
	v_mov_b64_e32 v[54:55], 0
	v_mov_b64_e32 v[8:9], 0
	v_mov_b64_e32 v[10:11], 0
	v_mov_b64_e32 v[12:13], 0
	v_mov_b64_e32 v[14:15], 0
	v_mov_b64_e32 v[24:25], 0
	v_mov_b64_e32 v[26:27], 0
	v_mov_b64_e32 v[28:29], 0
	v_mov_b64_e32 v[30:31], 0
	v_mov_b64_e32 v[40:41], 0
	v_mov_b64_e32 v[42:43], 0
	v_mov_b64_e32 v[44:45], 0
	v_mov_b64_e32 v[46:47], 0
	v_mov_b64_e32 v[56:57], 0
	v_mov_b64_e32 v[58:59], 0
	v_mov_b64_e32 v[60:61], 0
	v_mov_b64_e32 v[62:63], 0
	v_mov_b64_e32 v[64:65], 0
	v_mov_b64_e32 v[66:67], 0
	v_mov_b64_e32 v[68:69], 0
	v_mov_b64_e32 v[70:71], 0
	v_mov_b64_e32 v[80:81], 0
	v_mov_b64_e32 v[82:83], 0
	v_mov_b64_e32 v[84:85], 0
	v_mov_b64_e32 v[86:87], 0
	v_mov_b64_e32 v[96:97], 0
	v_mov_b64_e32 v[98:99], 0
	v_mov_b64_e32 v[100:101], 0
	v_mov_b64_e32 v[102:103], 0
	v_mov_b64_e32 v[112:113], 0
	v_mov_b64_e32 v[114:115], 0
	v_mov_b64_e32 v[116:117], 0
	v_mov_b64_e32 v[118:119], 0
	v_mov_b64_e32 v[72:73], 0
	v_mov_b64_e32 v[74:75], 0
	v_mov_b64_e32 v[76:77], 0
	v_mov_b64_e32 v[78:79], 0
	v_mov_b64_e32 v[88:89], 0
	v_mov_b64_e32 v[90:91], 0
	v_mov_b64_e32 v[92:93], 0
	v_mov_b64_e32 v[94:95], 0
	v_mov_b64_e32 v[104:105], 0
	v_mov_b64_e32 v[106:107], 0
	v_mov_b64_e32 v[108:109], 0
	v_mov_b64_e32 v[110:111], 0
	v_mov_b64_e32 v[120:121], 0
	v_mov_b64_e32 v[122:123], 0
	v_mov_b64_e32 v[124:125], 0
	v_mov_b64_e32 v[126:127], 0

.LBB0_827:
	s_add_i32 s3, s60, -2
	s_add_u32 s19, s44, 0x100
	s_addc_u32 s61, s45, 0
	s_add_u32 s44, s48, 0x40080
	v_mov_b32_e32 v0, 0
	s_addc_u32 s45, s49, 0
	s_mov_b32 s48, 0
	v_mov_b32_e32 v1, v0
	v_mov_b64_e32 v[2:3], 0
	v_mov_b64_e32 v[4:5], 0
	v_mov_b64_e32 v[6:7], 0
	v_mov_b64_e32 v[16:17], 0
	v_mov_b64_e32 v[18:19], 0
	v_mov_b64_e32 v[20:21], 0
	v_mov_b64_e32 v[22:23], 0
	v_mov_b64_e32 v[32:33], 0
	v_mov_b64_e32 v[34:35], 0
	v_mov_b64_e32 v[36:37], 0
	v_mov_b64_e32 v[38:39], 0
	v_mov_b64_e32 v[48:49], 0
	v_mov_b64_e32 v[50:51], 0
	v_mov_b64_e32 v[52:53], 0
	v_mov_b64_e32 v[54:55], 0
	v_mov_b64_e32 v[8:9], 0
	v_mov_b64_e32 v[10:11], 0
	v_mov_b64_e32 v[12:13], 0
	v_mov_b64_e32 v[14:15], 0
	v_mov_b64_e32 v[24:25], 0
	v_mov_b64_e32 v[26:27], 0
	v_mov_b64_e32 v[28:29], 0
	v_mov_b64_e32 v[30:31], 0
	v_mov_b64_e32 v[40:41], 0
	v_mov_b64_e32 v[42:43], 0
	v_mov_b64_e32 v[44:45], 0
	v_mov_b64_e32 v[46:47], 0
	v_mov_b64_e32 v[56:57], 0
	v_mov_b64_e32 v[58:59], 0
	v_mov_b64_e32 v[60:61], 0
	v_mov_b64_e32 v[62:63], 0
	v_mov_b64_e32 v[64:65], 0
	v_mov_b64_e32 v[66:67], 0
	v_mov_b64_e32 v[68:69], 0
	v_mov_b64_e32 v[70:71], 0
	v_mov_b64_e32 v[80:81], 0
	v_mov_b64_e32 v[82:83], 0
	v_mov_b64_e32 v[84:85], 0
	v_mov_b64_e32 v[86:87], 0
	v_mov_b64_e32 v[96:97], 0
	v_mov_b64_e32 v[98:99], 0
	v_mov_b64_e32 v[100:101], 0
	v_mov_b64_e32 v[102:103], 0
	v_mov_b64_e32 v[130:131], 0
	v_mov_b64_e32 v[132:133], 0
	v_mov_b64_e32 v[134:135], 0
	v_mov_b64_e32 v[136:137], 0
	v_mov_b64_e32 v[72:73], 0
	v_mov_b64_e32 v[74:75], 0
	v_mov_b64_e32 v[76:77], 0
	v_mov_b64_e32 v[78:79], 0
	v_mov_b64_e32 v[88:89], 0
	v_mov_b64_e32 v[90:91], 0
	v_mov_b64_e32 v[92:93], 0
	v_mov_b64_e32 v[94:95], 0
	v_mov_b64_e32 v[104:105], 0
	v_mov_b64_e32 v[106:107], 0
	v_mov_b64_e32 v[108:109], 0
	v_mov_b64_e32 v[110:111], 0
	v_mov_b64_e32 v[138:139], 0
	v_mov_b64_e32 v[140:141], 0
	v_mov_b64_e32 v[142:143], 0
	v_mov_b64_e32 v[144:145], 0

.LBB0_832:
	v_mov_b32_e32 v145, 0
	v_mov_b32_e32 v144, v145
	v_mov_b64_e32 v[142:143], 0
	v_mov_b64_e32 v[140:141], 0
	v_mov_b64_e32 v[138:139], 0
	v_mov_b64_e32 v[110:111], 0
	v_mov_b64_e32 v[108:109], 0
	v_mov_b64_e32 v[106:107], 0
	v_mov_b64_e32 v[104:105], 0
	v_mov_b64_e32 v[94:95], 0
	v_mov_b64_e32 v[92:93], 0
	v_mov_b64_e32 v[90:91], 0
	v_mov_b64_e32 v[88:89], 0
	v_mov_b64_e32 v[78:79], 0
	v_mov_b64_e32 v[76:77], 0
	v_mov_b64_e32 v[74:75], 0
	v_mov_b64_e32 v[72:73], 0
	v_mov_b64_e32 v[136:137], 0
	v_mov_b64_e32 v[134:135], 0
	v_mov_b64_e32 v[132:133], 0
	v_mov_b64_e32 v[130:131], 0
	v_mov_b64_e32 v[102:103], 0
	v_mov_b64_e32 v[100:101], 0
	v_mov_b64_e32 v[98:99], 0
	v_mov_b64_e32 v[96:97], 0
	v_mov_b64_e32 v[86:87], 0
	v_mov_b64_e32 v[84:85], 0
	v_mov_b64_e32 v[82:83], 0
	v_mov_b64_e32 v[80:81], 0
	v_mov_b64_e32 v[70:71], 0
	v_mov_b64_e32 v[68:69], 0
	v_mov_b64_e32 v[66:67], 0
	v_mov_b64_e32 v[64:65], 0
	v_mov_b64_e32 v[62:63], 0
	v_mov_b64_e32 v[60:61], 0
	v_mov_b64_e32 v[58:59], 0
	v_mov_b64_e32 v[56:57], 0
	v_mov_b64_e32 v[46:47], 0
	v_mov_b64_e32 v[44:45], 0
	v_mov_b64_e32 v[42:43], 0
	v_mov_b64_e32 v[40:41], 0
	v_mov_b64_e32 v[30:31], 0
	v_mov_b64_e32 v[28:29], 0
	v_mov_b64_e32 v[26:27], 0
	v_mov_b64_e32 v[24:25], 0
	v_mov_b64_e32 v[14:15], 0
	v_mov_b64_e32 v[12:13], 0
	v_mov_b64_e32 v[10:11], 0
	v_mov_b64_e32 v[8:9], 0
	v_mov_b64_e32 v[54:55], 0
	v_mov_b64_e32 v[52:53], 0
	v_mov_b64_e32 v[50:51], 0
	v_mov_b64_e32 v[48:49], 0
	v_mov_b64_e32 v[38:39], 0
	v_mov_b64_e32 v[36:37], 0
	v_mov_b64_e32 v[34:35], 0
	v_mov_b64_e32 v[32:33], 0
	v_mov_b64_e32 v[22:23], 0
	v_mov_b64_e32 v[20:21], 0
	v_mov_b64_e32 v[18:19], 0
	v_mov_b64_e32 v[16:17], 0
	v_mov_b64_e32 v[6:7], 0
	v_mov_b64_e32 v[4:5], 0
	v_mov_b64_e32 v[2:3], 0
	v_mov_b64_e32 v[0:1], 0

.LBB0_915:
	s_ashr_i32 s45, s44, 31
	s_lshl_b64 s[8:9], s[44:45], 19
	v_readlane_b32 s38, v251, 3
	v_readlane_b32 s39, v251, 4
	s_add_u32 s46, s38, s8
	s_addc_u32 s47, s39, s9
	s_ashr_i32 s19, s18, 31
	s_lshl_b64 s[8:9], s[18:19], 19
	v_mov_b64_e32 v[0:1], 0x100
	s_add_u32 s48, s6, s8
	v_mov_b32_e32 v127, 0
	v_cmp_lt_i64_e64 s[0:1], s[0:1], v[0:1]
	s_addc_u32 s49, s7, s9
	s_andn2_b64 vcc, exec, s[2:3]
	v_mov_b32_e32 v126, v127
	v_mov_b64_e32 v[124:125], 0
	v_mov_b64_e32 v[122:123], 0
	v_mov_b64_e32 v[120:121], 0
	v_mov_b64_e32 v[110:111], 0
	v_mov_b64_e32 v[108:109], 0
	v_mov_b64_e32 v[106:107], 0
	v_mov_b64_e32 v[104:105], 0
	v_mov_b64_e32 v[94:95], 0
	v_mov_b64_e32 v[92:93], 0
	v_mov_b64_e32 v[90:91], 0
	v_mov_b64_e32 v[88:89], 0
	v_mov_b64_e32 v[78:79], 0
	v_mov_b64_e32 v[76:77], 0
	v_mov_b64_e32 v[74:75], 0
	v_mov_b64_e32 v[72:73], 0
	v_mov_b64_e32 v[118:119], 0
	v_mov_b64_e32 v[116:117], 0
	v_mov_b64_e32 v[114:115], 0
	v_mov_b64_e32 v[112:113], 0
	v_mov_b64_e32 v[102:103], 0
	v_mov_b64_e32 v[100:101], 0
	v_mov_b64_e32 v[98:99], 0
	v_mov_b64_e32 v[96:97], 0
	v_mov_b64_e32 v[86:87], 0
	v_mov_b64_e32 v[84:85], 0
	v_mov_b64_e32 v[82:83], 0
	v_mov_b64_e32 v[80:81], 0
	v_mov_b64_e32 v[70:71], 0
	v_mov_b64_e32 v[68:69], 0
	v_mov_b64_e32 v[66:67], 0
	v_mov_b64_e32 v[64:65], 0
	v_mov_b64_e32 v[62:63], 0
	v_mov_b64_e32 v[60:61], 0
	v_mov_b64_e32 v[58:59], 0
	v_mov_b64_e32 v[56:57], 0
	v_mov_b64_e32 v[46:47], 0
	v_mov_b64_e32 v[44:45], 0
	v_mov_b64_e32 v[42:43], 0
	v_mov_b64_e32 v[40:41], 0
	v_mov_b64_e32 v[30:31], 0
	v_mov_b64_e32 v[28:29], 0
	v_mov_b64_e32 v[26:27], 0
	v_mov_b64_e32 v[24:25], 0
	v_mov_b64_e32 v[14:15], 0
	v_mov_b64_e32 v[12:13], 0
	v_mov_b64_e32 v[10:11], 0
	v_mov_b64_e32 v[8:9], 0
	v_mov_b64_e32 v[54:55], 0
	v_mov_b64_e32 v[52:53], 0
	v_mov_b64_e32 v[50:51], 0
	v_mov_b64_e32 v[48:49], 0
	v_mov_b64_e32 v[38:39], 0
	v_mov_b64_e32 v[36:37], 0
	v_mov_b64_e32 v[34:35], 0
	v_mov_b64_e32 v[32:33], 0
	v_mov_b64_e32 v[22:23], 0
	v_mov_b64_e32 v[20:21], 0
	v_mov_b64_e32 v[18:19], 0
	v_mov_b64_e32 v[16:17], 0
	v_mov_b64_e32 v[6:7], 0
	v_mov_b64_e32 v[4:5], 0
	v_mov_b64_e32 v[2:3], 0
	v_mov_b64_e32 v[0:1], 0
	s_cbranch_vccnz .LBB0_919
	s_and_b64 s[0:1], s[0:1], exec
	s_cselect_b32 s8, s47, s53
	s_cselect_b32 s9, s46, s52
	s_cselect_b32 s19, s49, s51
	s_cselect_b32 s45, s48, s50
	s_add_u32 s63, s50, 0x100
	s_addc_u32 s64, s51, 0
	s_add_u32 s0, s52, 0x40080
	v_mov_b32_e32 v0, 0
	s_addc_u32 s1, s53, 0
	s_mov_b32 s50, 0
	v_mov_b32_e32 v1, v0
	v_mov_b64_e32 v[2:3], 0
	v_mov_b64_e32 v[4:5], 0
	v_mov_b64_e32 v[6:7], 0
	v_mov_b64_e32 v[16:17], 0
	v_mov_b64_e32 v[18:19], 0
	v_mov_b64_e32 v[20:21], 0
	v_mov_b64_e32 v[22:23], 0
	v_mov_b64_e32 v[32:33], 0
	v_mov_b64_e32 v[34:35], 0
	v_mov_b64_e32 v[36:37], 0
	v_mov_b64_e32 v[38:39], 0
	v_mov_b64_e32 v[48:49], 0
	v_mov_b64_e32 v[50:51], 0
	v_mov_b64_e32 v[52:53], 0
	v_mov_b64_e32 v[54:55], 0
	v_mov_b64_e32 v[8:9], 0
	v_mov_b64_e32 v[10:11], 0
	v_mov_b64_e32 v[12:13], 0
	v_mov_b64_e32 v[14:15], 0
	v_mov_b64_e32 v[24:25], 0
	v_mov_b64_e32 v[26:27], 0
	v_mov_b64_e32 v[28:29], 0
	v_mov_b64_e32 v[30:31], 0
	v_mov_b64_e32 v[40:41], 0
	v_mov_b64_e32 v[42:43], 0
	v_mov_b64_e32 v[44:45], 0
	v_mov_b64_e32 v[46:47], 0
	v_mov_b64_e32 v[56:57], 0
	v_mov_b64_e32 v[58:59], 0
	v_mov_b64_e32 v[60:61], 0
	v_mov_b64_e32 v[62:63], 0
	v_mov_b64_e32 v[64:65], 0
	v_mov_b64_e32 v[66:67], 0
	v_mov_b64_e32 v[68:69], 0
	v_mov_b64_e32 v[70:71], 0
	v_mov_b64_e32 v[80:81], 0
	v_mov_b64_e32 v[82:83], 0
	v_mov_b64_e32 v[84:85], 0
	v_mov_b64_e32 v[86:87], 0
	v_mov_b64_e32 v[96:97], 0
	v_mov_b64_e32 v[98:99], 0
	v_mov_b64_e32 v[100:101], 0
	v_mov_b64_e32 v[102:103], 0
	v_mov_b64_e32 v[112:113], 0
	v_mov_b64_e32 v[114:115], 0
	v_mov_b64_e32 v[116:117], 0
	v_mov_b64_e32 v[118:119], 0
	v_mov_b64_e32 v[72:73], 0
	v_mov_b64_e32 v[74:75], 0
	v_mov_b64_e32 v[76:77], 0
	v_mov_b64_e32 v[78:79], 0
	v_mov_b64_e32 v[88:89], 0
	v_mov_b64_e32 v[90:91], 0
	v_mov_b64_e32 v[92:93], 0
	v_mov_b64_e32 v[94:95], 0
	v_mov_b64_e32 v[104:105], 0
	v_mov_b64_e32 v[106:107], 0
	v_mov_b64_e32 v[108:109], 0
	v_mov_b64_e32 v[110:111], 0
	v_mov_b64_e32 v[120:121], 0
	v_mov_b64_e32 v[122:123], 0
	v_mov_b64_e32 v[124:125], 0
	v_mov_b64_e32 v[126:127], 0

.LBB0_1018:
	s_ashr_i32 s55, s54, 31
	s_lshl_b64 s[8:9], s[54:55], 19
	v_readlane_b32 s20, v251, 3
	v_readlane_b32 s21, v251, 4
	s_add_u32 s58, s20, s8
	s_addc_u32 s59, s21, s9
	s_ashr_i32 s53, s52, 31
	s_lshl_b64 s[8:9], s[52:53], 19
	s_add_u32 s60, s5, s8
	v_mov_b32_e32 v127, 0
	s_addc_u32 s61, s6, s9
	s_andn2_b64 vcc, exec, s[0:1]
	v_mov_b32_e32 v126, v127
	v_mov_b32_e32 v125, v127
	v_mov_b32_e32 v124, v127
	v_mov_b32_e32 v123, v127
	v_mov_b32_e32 v122, v127
	v_mov_b32_e32 v121, v127
	v_mov_b32_e32 v120, v127
	v_mov_b32_e32 v111, v127
	v_mov_b32_e32 v110, v127
	v_mov_b32_e32 v109, v127
	v_mov_b32_e32 v108, v127
	v_mov_b32_e32 v107, v127
	v_mov_b32_e32 v106, v127
	s_waitcnt lgkmcnt(0)
	v_mov_b32_e32 v105, v127
	v_mov_b32_e32 v104, v127
	v_mov_b32_e32 v95, v127
	v_mov_b32_e32 v94, v127
	v_mov_b32_e32 v93, v127
	v_mov_b32_e32 v92, v127
	v_mov_b32_e32 v91, v127
	v_mov_b32_e32 v90, v127
	v_mov_b32_e32 v89, v127
	v_mov_b32_e32 v88, v127
	v_mov_b32_e32 v79, v127
	v_mov_b32_e32 v78, v127
	v_mov_b32_e32 v77, v127
	v_mov_b32_e32 v76, v127
	v_mov_b32_e32 v75, v127
	v_mov_b32_e32 v74, v127
	v_mov_b32_e32 v73, v127
	v_mov_b32_e32 v72, v127
	v_mov_b32_e32 v119, v127
	v_mov_b32_e32 v118, v127
	v_mov_b32_e32 v117, v127
	v_mov_b32_e32 v116, v127
	v_mov_b32_e32 v115, v127
	v_mov_b32_e32 v114, v127
	v_mov_b32_e32 v113, v127
	v_mov_b32_e32 v112, v127
	v_mov_b32_e32 v103, v127
	v_mov_b32_e32 v102, v127
	v_mov_b32_e32 v101, v127
	v_mov_b32_e32 v100, v127
	v_mov_b32_e32 v99, v127
	v_mov_b32_e32 v98, v127
	v_mov_b32_e32 v97, v127
	v_mov_b32_e32 v96, v127
	v_mov_b32_e32 v87, v127
	v_mov_b32_e32 v86, v127
	v_mov_b32_e32 v85, v127
	v_mov_b32_e32 v84, v127
	v_mov_b32_e32 v83, v127
	v_mov_b32_e32 v82, v127
	v_mov_b32_e32 v81, v127
	v_mov_b32_e32 v80, v127
	v_mov_b32_e32 v71, v127
	v_mov_b32_e32 v70, v127
	v_mov_b32_e32 v69, v127
	v_mov_b32_e32 v68, v127
	v_mov_b32_e32 v67, v127
	v_mov_b32_e32 v66, v127
	v_mov_b32_e32 v65, v127
	v_mov_b32_e32 v64, v127
	v_mov_b32_e32 v63, v127
	v_mov_b32_e32 v62, v127
	v_mov_b32_e32 v61, v127
	v_mov_b32_e32 v60, v127
	v_mov_b32_e32 v59, v127
	v_mov_b32_e32 v58, v127
	v_mov_b32_e32 v57, v127
	v_mov_b32_e32 v56, v127
	v_mov_b32_e32 v47, v127
	v_mov_b32_e32 v46, v127
	v_mov_b32_e32 v45, v127
	v_mov_b32_e32 v44, v127
	v_mov_b32_e32 v43, v127
	v_mov_b32_e32 v42, v127
	v_mov_b32_e32 v41, v127
	v_mov_b32_e32 v40, v127
	v_mov_b32_e32 v31, v127
	v_mov_b32_e32 v30, v127
	v_mov_b32_e32 v29, v127
	v_mov_b32_e32 v28, v127
	v_mov_b32_e32 v27, v127
	v_mov_b32_e32 v26, v127
	v_mov_b32_e32 v25, v127
	v_mov_b32_e32 v24, v127
	v_mov_b32_e32 v15, v127
	v_mov_b32_e32 v14, v127
	v_mov_b32_e32 v13, v127
	v_mov_b32_e32 v12, v127
	v_mov_b32_e32 v11, v127
	v_mov_b32_e32 v10, v127
	v_mov_b32_e32 v9, v127
	v_mov_b32_e32 v8, v127
	v_mov_b32_e32 v55, v127
	v_mov_b32_e32 v54, v127
	v_mov_b32_e32 v53, v127
	v_mov_b32_e32 v52, v127
	v_mov_b32_e32 v51, v127
	v_mov_b32_e32 v50, v127
	v_mov_b32_e32 v49, v127
	v_mov_b32_e32 v48, v127
	v_mov_b32_e32 v39, v127
	v_mov_b32_e32 v38, v127
	v_mov_b32_e32 v37, v127
	v_mov_b32_e32 v36, v127
	v_mov_b32_e32 v35, v127
	v_mov_b32_e32 v34, v127
	v_mov_b32_e32 v33, v127
	v_mov_b32_e32 v32, v127
	v_mov_b32_e32 v23, v127
	v_mov_b32_e32 v22, v127
	v_mov_b32_e32 v21, v127
	v_mov_b32_e32 v20, v127
	v_mov_b32_e32 v19, v127
	v_mov_b32_e32 v18, v127
	v_mov_b32_e32 v17, v127
	v_mov_b32_e32 v16, v127
	v_mov_b32_e32 v7, v127
	v_mov_b32_e32 v6, v127
	v_mov_b32_e32 v5, v127
	v_mov_b32_e32 v4, v127
	v_mov_b32_e32 v3, v127
	v_mov_b32_e32 v2, v127
	v_mov_b32_e32 v1, v127
	v_mov_b32_e32 v0, v127
	s_cbranch_vccnz .LBB0_1022
	v_mov_b64_e32 v[0:1], 0x108
	v_cmp_lt_i64_e32 vcc, s[50:51], v[0:1]
	s_and_b64 s[8:9], vcc, exec
	s_cselect_b32 s3, s59, s49
	s_cselect_b32 s8, s58, s48
	s_cselect_b32 s9, s61, s47
	s_cselect_b32 s19, s60, s46
	s_add_u32 s20, s46, 0x100
	s_addc_u32 s21, s47, 0
	s_add_u32 s46, s48, 0x40080
	v_mov_b32_e32 v0, 0
	s_addc_u32 s47, s49, 0
	s_mov_b32 s22, 0
	v_mov_b32_e32 v1, v0
	v_mov_b64_e32 v[2:3], 0
	v_mov_b64_e32 v[4:5], 0
	v_mov_b64_e32 v[6:7], 0
	v_mov_b64_e32 v[16:17], 0
	v_mov_b64_e32 v[18:19], 0
	v_mov_b64_e32 v[20:21], 0
	v_mov_b64_e32 v[22:23], 0
	v_mov_b64_e32 v[32:33], 0
	v_mov_b64_e32 v[34:35], 0
	v_mov_b64_e32 v[36:37], 0
	v_mov_b64_e32 v[38:39], 0
	v_mov_b64_e32 v[48:49], 0
	v_mov_b64_e32 v[50:51], 0
	v_mov_b64_e32 v[52:53], 0
	v_mov_b64_e32 v[54:55], 0
	v_mov_b64_e32 v[8:9], 0
	v_mov_b64_e32 v[10:11], 0
	v_mov_b64_e32 v[12:13], 0
	v_mov_b64_e32 v[14:15], 0
	v_mov_b64_e32 v[24:25], 0
	v_mov_b64_e32 v[26:27], 0
	v_mov_b64_e32 v[28:29], 0
	v_mov_b64_e32 v[30:31], 0
	v_mov_b64_e32 v[40:41], 0
	v_mov_b64_e32 v[42:43], 0
	v_mov_b64_e32 v[44:45], 0
	v_mov_b64_e32 v[46:47], 0
	v_mov_b64_e32 v[56:57], 0
	v_mov_b64_e32 v[58:59], 0
	v_mov_b64_e32 v[60:61], 0
	v_mov_b64_e32 v[62:63], 0
	v_mov_b64_e32 v[64:65], 0
	v_mov_b64_e32 v[66:67], 0
	v_mov_b64_e32 v[68:69], 0
	v_mov_b64_e32 v[70:71], 0
	v_mov_b64_e32 v[80:81], 0
	v_mov_b64_e32 v[82:83], 0
	v_mov_b64_e32 v[84:85], 0
	v_mov_b64_e32 v[86:87], 0
	v_mov_b64_e32 v[96:97], 0
	v_mov_b64_e32 v[98:99], 0
	v_mov_b64_e32 v[100:101], 0
	v_mov_b64_e32 v[102:103], 0
	v_mov_b64_e32 v[112:113], 0
	v_mov_b64_e32 v[114:115], 0
	v_mov_b64_e32 v[116:117], 0
	v_mov_b64_e32 v[118:119], 0
	v_mov_b64_e32 v[72:73], 0
	v_mov_b64_e32 v[74:75], 0
	v_mov_b64_e32 v[76:77], 0
	v_mov_b64_e32 v[78:79], 0
	v_mov_b64_e32 v[88:89], 0
	v_mov_b64_e32 v[90:91], 0
	v_mov_b64_e32 v[92:93], 0
	v_mov_b64_e32 v[94:95], 0
	v_mov_b64_e32 v[104:105], 0
	v_mov_b64_e32 v[106:107], 0
	v_mov_b64_e32 v[108:109], 0
	v_mov_b64_e32 v[110:111], 0
	v_mov_b64_e32 v[120:121], 0
	v_mov_b64_e32 v[122:123], 0
	v_mov_b64_e32 v[124:125], 0
	v_mov_b64_e32 v[126:127], 0

.LBB0_1419:
	s_ashr_i32 s79, s78, 31
	s_lshl_b64 s[8:9], s[78:79], 17
	s_add_u32 s84, s5, s8
	v_mov_b32_e32 v127, 0
	s_addc_u32 s85, s6, s9
	s_andn2_b64 vcc, exec, s[72:73]
	v_mov_b32_e32 v126, v127
	v_mov_b64_e32 v[124:125], 0
	v_mov_b64_e32 v[122:123], 0
	v_mov_b64_e32 v[120:121], 0
	v_mov_b64_e32 v[110:111], 0
	v_mov_b64_e32 v[108:109], 0
	v_mov_b64_e32 v[106:107], 0
	v_mov_b64_e32 v[104:105], 0
	v_mov_b64_e32 v[94:95], 0
	v_mov_b64_e32 v[92:93], 0
	v_mov_b64_e32 v[90:91], 0
	v_mov_b64_e32 v[88:89], 0
	v_mov_b64_e32 v[78:79], 0
	v_mov_b64_e32 v[76:77], 0
	v_mov_b64_e32 v[74:75], 0
	v_mov_b64_e32 v[72:73], 0
	v_mov_b64_e32 v[118:119], 0
	v_mov_b64_e32 v[116:117], 0
	v_mov_b64_e32 v[114:115], 0
	v_mov_b64_e32 v[112:113], 0
	v_mov_b64_e32 v[102:103], 0
	v_mov_b64_e32 v[100:101], 0
	v_mov_b64_e32 v[98:99], 0
	v_mov_b64_e32 v[96:97], 0
	v_mov_b64_e32 v[86:87], 0
	v_mov_b64_e32 v[84:85], 0
	v_mov_b64_e32 v[82:83], 0
	v_mov_b64_e32 v[80:81], 0
	v_mov_b64_e32 v[70:71], 0
	v_mov_b64_e32 v[68:69], 0
	v_mov_b64_e32 v[66:67], 0
	v_mov_b64_e32 v[64:65], 0
	v_mov_b64_e32 v[62:63], 0
	v_mov_b64_e32 v[60:61], 0
	v_mov_b64_e32 v[58:59], 0
	v_mov_b64_e32 v[56:57], 0
	v_mov_b64_e32 v[46:47], 0
	v_mov_b64_e32 v[44:45], 0
	v_mov_b64_e32 v[42:43], 0
	v_mov_b64_e32 v[40:41], 0
	v_mov_b64_e32 v[30:31], 0
	v_mov_b64_e32 v[28:29], 0
	v_mov_b64_e32 v[26:27], 0
	v_mov_b64_e32 v[24:25], 0
	v_mov_b64_e32 v[14:15], 0
	v_mov_b64_e32 v[12:13], 0
	v_mov_b64_e32 v[10:11], 0
	v_mov_b64_e32 v[8:9], 0
	v_mov_b64_e32 v[54:55], 0
	v_mov_b64_e32 v[52:53], 0
	v_mov_b64_e32 v[50:51], 0
	v_mov_b64_e32 v[48:49], 0
	v_mov_b64_e32 v[38:39], 0
	v_mov_b64_e32 v[36:37], 0
	v_mov_b64_e32 v[34:35], 0
	v_mov_b64_e32 v[32:33], 0
	v_mov_b64_e32 v[22:23], 0
	v_mov_b64_e32 v[20:21], 0
	v_mov_b64_e32 v[18:19], 0
	v_mov_b64_e32 v[16:17], 0
	v_mov_b64_e32 v[6:7], 0
	v_mov_b64_e32 v[4:5], 0
	v_mov_b64_e32 v[2:3], 0
	v_mov_b64_e32 v[0:1], 0
	s_cbranch_vccnz .LBB0_1422
	s_and_b64 s[8:9], s[46:47], exec
	s_cselect_b32 s1, s85, s19
	s_cselect_b32 s8, s84, s18
	s_add_u32 s9, s18, 0x100
	v_mov_b32_e32 v0, 0
	s_addc_u32 s51, s19, 0
	s_mov_b32 s46, 0
	v_mov_b32_e32 v1, v0
	v_mov_b64_e32 v[2:3], 0
	v_mov_b64_e32 v[4:5], 0
	v_mov_b64_e32 v[6:7], 0
	v_mov_b64_e32 v[16:17], 0
	v_mov_b64_e32 v[18:19], 0
	v_mov_b64_e32 v[20:21], 0
	v_mov_b64_e32 v[22:23], 0
	v_mov_b64_e32 v[32:33], 0
	v_mov_b64_e32 v[34:35], 0
	v_mov_b64_e32 v[36:37], 0
	v_mov_b64_e32 v[38:39], 0
	v_mov_b64_e32 v[48:49], 0
	v_mov_b64_e32 v[50:51], 0
	v_mov_b64_e32 v[52:53], 0
	v_mov_b64_e32 v[54:55], 0
	v_mov_b64_e32 v[8:9], 0
	v_mov_b64_e32 v[10:11], 0
	v_mov_b64_e32 v[12:13], 0
	v_mov_b64_e32 v[14:15], 0
	v_mov_b64_e32 v[24:25], 0
	v_mov_b64_e32 v[26:27], 0
	v_mov_b64_e32 v[28:29], 0
	v_mov_b64_e32 v[30:31], 0
	v_mov_b64_e32 v[40:41], 0
	v_mov_b64_e32 v[42:43], 0
	v_mov_b64_e32 v[44:45], 0
	v_mov_b64_e32 v[46:47], 0
	v_mov_b64_e32 v[56:57], 0
	v_mov_b64_e32 v[58:59], 0
	v_mov_b64_e32 v[60:61], 0
	v_mov_b64_e32 v[62:63], 0
	v_mov_b64_e32 v[64:65], 0
	v_mov_b64_e32 v[66:67], 0
	v_mov_b64_e32 v[68:69], 0
	v_mov_b64_e32 v[70:71], 0
	v_mov_b64_e32 v[80:81], 0
	v_mov_b64_e32 v[82:83], 0
	v_mov_b64_e32 v[84:85], 0
	v_mov_b64_e32 v[86:87], 0
	v_mov_b64_e32 v[96:97], 0
	v_mov_b64_e32 v[98:99], 0
	v_mov_b64_e32 v[100:101], 0
	v_mov_b64_e32 v[102:103], 0
	v_mov_b64_e32 v[112:113], 0
	v_mov_b64_e32 v[114:115], 0
	v_mov_b64_e32 v[116:117], 0
	v_mov_b64_e32 v[118:119], 0
	v_mov_b64_e32 v[72:73], 0
	v_mov_b64_e32 v[74:75], 0
	v_mov_b64_e32 v[76:77], 0
	v_mov_b64_e32 v[78:79], 0
	v_mov_b64_e32 v[88:89], 0
	v_mov_b64_e32 v[90:91], 0
	v_mov_b64_e32 v[92:93], 0
	v_mov_b64_e32 v[94:95], 0
	v_mov_b64_e32 v[104:105], 0
	v_mov_b64_e32 v[106:107], 0
	v_mov_b64_e32 v[108:109], 0
	v_mov_b64_e32 v[110:111], 0
	v_mov_b64_e32 v[120:121], 0
	v_mov_b64_e32 v[122:123], 0
	v_mov_b64_e32 v[124:125], 0
	v_mov_b64_e32 v[126:127], 0

.LBB0_1564:
	s_ashr_i32 s53, s52, 31
	s_lshl_b64 s[8:9], s[52:53], 17
	s_add_u32 s66, s7, s8
	v_mov_b32_e32 v127, 0
	s_addc_u32 s67, s26, s9
	s_andn2_b64 vcc, exec, s[50:51]
	v_mov_b32_e32 v126, v127
	v_mov_b64_e32 v[124:125], 0
	v_mov_b64_e32 v[122:123], 0
	v_mov_b64_e32 v[120:121], 0
	v_mov_b64_e32 v[110:111], 0
	v_mov_b64_e32 v[108:109], 0
	v_mov_b64_e32 v[106:107], 0
	v_mov_b64_e32 v[104:105], 0
	v_mov_b64_e32 v[94:95], 0
	v_mov_b64_e32 v[92:93], 0
	v_mov_b64_e32 v[90:91], 0
	v_mov_b64_e32 v[88:89], 0
	v_mov_b64_e32 v[78:79], 0
	v_mov_b64_e32 v[76:77], 0
	v_mov_b64_e32 v[74:75], 0
	v_mov_b64_e32 v[72:73], 0
	v_mov_b64_e32 v[118:119], 0
	v_mov_b64_e32 v[116:117], 0
	v_mov_b64_e32 v[114:115], 0
	v_mov_b64_e32 v[112:113], 0
	v_mov_b64_e32 v[102:103], 0
	v_mov_b64_e32 v[100:101], 0
	v_mov_b64_e32 v[98:99], 0
	v_mov_b64_e32 v[96:97], 0
	v_mov_b64_e32 v[86:87], 0
	v_mov_b64_e32 v[84:85], 0
	v_mov_b64_e32 v[82:83], 0
	v_mov_b64_e32 v[80:81], 0
	v_mov_b64_e32 v[70:71], 0
	v_mov_b64_e32 v[68:69], 0
	v_mov_b64_e32 v[66:67], 0
	v_mov_b64_e32 v[64:65], 0
	v_mov_b64_e32 v[62:63], 0
	v_mov_b64_e32 v[60:61], 0
	v_mov_b64_e32 v[58:59], 0
	v_mov_b64_e32 v[56:57], 0
	v_mov_b64_e32 v[46:47], 0
	v_mov_b64_e32 v[44:45], 0
	v_mov_b64_e32 v[42:43], 0
	v_mov_b64_e32 v[40:41], 0
	v_mov_b64_e32 v[30:31], 0
	v_mov_b64_e32 v[28:29], 0
	v_mov_b64_e32 v[26:27], 0
	v_mov_b64_e32 v[24:25], 0
	v_mov_b64_e32 v[14:15], 0
	v_mov_b64_e32 v[12:13], 0
	v_mov_b64_e32 v[10:11], 0
	v_mov_b64_e32 v[8:9], 0
	v_mov_b64_e32 v[54:55], 0
	v_mov_b64_e32 v[52:53], 0
	v_mov_b64_e32 v[50:51], 0
	v_mov_b64_e32 v[48:49], 0
	v_mov_b64_e32 v[38:39], 0
	v_mov_b64_e32 v[36:37], 0
	v_mov_b64_e32 v[34:35], 0
	v_mov_b64_e32 v[32:33], 0
	v_mov_b64_e32 v[22:23], 0
	v_mov_b64_e32 v[20:21], 0
	v_mov_b64_e32 v[18:19], 0
	v_mov_b64_e32 v[16:17], 0
	v_mov_b64_e32 v[6:7], 0
	v_mov_b64_e32 v[4:5], 0
	v_mov_b64_e32 v[2:3], 0
	v_mov_b64_e32 v[0:1], 0
	s_cbranch_vccnz .LBB0_1567
	s_and_b64 s[8:9], s[44:45], exec
	s_cselect_b32 s1, s67, s19
	s_cselect_b32 s8, s66, s18
	s_add_u32 s9, s18, 0x100
	v_mov_b32_e32 v0, 0
	s_addc_u32 s23, s19, 0
	s_mov_b32 s44, 0
	v_mov_b32_e32 v1, v0
	v_mov_b64_e32 v[2:3], 0
	v_mov_b64_e32 v[4:5], 0
	v_mov_b64_e32 v[6:7], 0
	v_mov_b64_e32 v[16:17], 0
	v_mov_b64_e32 v[18:19], 0
	v_mov_b64_e32 v[20:21], 0
	v_mov_b64_e32 v[22:23], 0
	v_mov_b64_e32 v[32:33], 0
	v_mov_b64_e32 v[34:35], 0
	v_mov_b64_e32 v[36:37], 0
	v_mov_b64_e32 v[38:39], 0
	v_mov_b64_e32 v[48:49], 0
	v_mov_b64_e32 v[50:51], 0
	v_mov_b64_e32 v[52:53], 0
	v_mov_b64_e32 v[54:55], 0
	v_mov_b64_e32 v[8:9], 0
	v_mov_b64_e32 v[10:11], 0
	v_mov_b64_e32 v[12:13], 0
	v_mov_b64_e32 v[14:15], 0
	v_mov_b64_e32 v[24:25], 0
	v_mov_b64_e32 v[26:27], 0
	v_mov_b64_e32 v[28:29], 0
	v_mov_b64_e32 v[30:31], 0
	v_mov_b64_e32 v[40:41], 0
	v_mov_b64_e32 v[42:43], 0
	v_mov_b64_e32 v[44:45], 0
	v_mov_b64_e32 v[46:47], 0
	v_mov_b64_e32 v[56:57], 0
	v_mov_b64_e32 v[58:59], 0
	v_mov_b64_e32 v[60:61], 0
	v_mov_b64_e32 v[62:63], 0
	v_mov_b64_e32 v[64:65], 0
	v_mov_b64_e32 v[66:67], 0
	v_mov_b64_e32 v[68:69], 0
	v_mov_b64_e32 v[70:71], 0
	v_mov_b64_e32 v[80:81], 0
	v_mov_b64_e32 v[82:83], 0
	v_mov_b64_e32 v[84:85], 0
	v_mov_b64_e32 v[86:87], 0
	v_mov_b64_e32 v[96:97], 0
	v_mov_b64_e32 v[98:99], 0
	v_mov_b64_e32 v[100:101], 0
	v_mov_b64_e32 v[102:103], 0
	v_mov_b64_e32 v[112:113], 0
	v_mov_b64_e32 v[114:115], 0
	v_mov_b64_e32 v[116:117], 0
	v_mov_b64_e32 v[118:119], 0
	v_mov_b64_e32 v[72:73], 0
	v_mov_b64_e32 v[74:75], 0
	v_mov_b64_e32 v[76:77], 0
	v_mov_b64_e32 v[78:79], 0
	v_mov_b64_e32 v[88:89], 0
	v_mov_b64_e32 v[90:91], 0
	v_mov_b64_e32 v[92:93], 0
	v_mov_b64_e32 v[94:95], 0
	v_mov_b64_e32 v[104:105], 0
	v_mov_b64_e32 v[106:107], 0
	v_mov_b64_e32 v[108:109], 0
	v_mov_b64_e32 v[110:111], 0
	v_mov_b64_e32 v[120:121], 0
	v_mov_b64_e32 v[122:123], 0
	v_mov_b64_e32 v[124:125], 0
	v_mov_b64_e32 v[126:127], 0

.LBB0_1975:
	s_ashr_i32 s51, s50, 31
	s_lshl_b64 s[8:9], s[50:51], 18
	s_add_u32 s52, s44, s8
	s_addc_u32 s53, s45, s9
	s_ashr_i32 s49, s48, 31
	s_lshl_b64 s[8:9], s[48:49], 18
	v_mov_b64_e32 v[0:1], 0x84
	s_add_u32 s54, s5, s8
	v_mov_b32_e32 v127, 0
	v_cmp_lt_i64_e64 s[0:1], s[0:1], v[0:1]
	s_addc_u32 s55, s6, s9
	s_andn2_b64 vcc, exec, s[46:47]
	v_mov_b32_e32 v126, v127
	v_mov_b64_e32 v[124:125], 0
	v_mov_b64_e32 v[122:123], 0
	v_mov_b64_e32 v[120:121], 0
	v_mov_b64_e32 v[110:111], 0
	v_mov_b64_e32 v[108:109], 0
	v_mov_b64_e32 v[106:107], 0
	v_mov_b64_e32 v[104:105], 0
	v_mov_b64_e32 v[94:95], 0
	v_mov_b64_e32 v[92:93], 0
	v_mov_b64_e32 v[90:91], 0
	v_mov_b64_e32 v[88:89], 0
	v_mov_b64_e32 v[78:79], 0
	v_mov_b64_e32 v[76:77], 0
	v_mov_b64_e32 v[74:75], 0
	v_mov_b64_e32 v[72:73], 0
	v_mov_b64_e32 v[118:119], 0
	v_mov_b64_e32 v[116:117], 0
	v_mov_b64_e32 v[114:115], 0
	v_mov_b64_e32 v[112:113], 0
	v_mov_b64_e32 v[102:103], 0
	v_mov_b64_e32 v[100:101], 0
	v_mov_b64_e32 v[98:99], 0
	v_mov_b64_e32 v[96:97], 0
	v_mov_b64_e32 v[86:87], 0
	v_mov_b64_e32 v[84:85], 0
	v_mov_b64_e32 v[82:83], 0
	v_mov_b64_e32 v[80:81], 0
	v_mov_b64_e32 v[70:71], 0
	v_mov_b64_e32 v[68:69], 0
	v_mov_b64_e32 v[66:67], 0
	v_mov_b64_e32 v[64:65], 0
	v_mov_b64_e32 v[62:63], 0
	v_mov_b64_e32 v[60:61], 0
	v_mov_b64_e32 v[58:59], 0
	v_mov_b64_e32 v[56:57], 0
	v_mov_b64_e32 v[46:47], 0
	v_mov_b64_e32 v[44:45], 0
	v_mov_b64_e32 v[42:43], 0
	v_mov_b64_e32 v[40:41], 0
	v_mov_b64_e32 v[30:31], 0
	v_mov_b64_e32 v[28:29], 0
	v_mov_b64_e32 v[26:27], 0
	v_mov_b64_e32 v[24:25], 0
	v_mov_b64_e32 v[14:15], 0
	v_mov_b64_e32 v[12:13], 0
	v_mov_b64_e32 v[10:11], 0
	v_mov_b64_e32 v[8:9], 0
	v_mov_b64_e32 v[54:55], 0
	v_mov_b64_e32 v[52:53], 0
	v_mov_b64_e32 v[50:51], 0
	v_mov_b64_e32 v[48:49], 0
	v_mov_b64_e32 v[38:39], 0
	v_mov_b64_e32 v[36:37], 0
	v_mov_b64_e32 v[34:35], 0
	v_mov_b64_e32 v[32:33], 0
	v_mov_b64_e32 v[22:23], 0
	v_mov_b64_e32 v[20:21], 0
	v_mov_b64_e32 v[18:19], 0
	v_mov_b64_e32 v[16:17], 0
	v_mov_b64_e32 v[6:7], 0
	v_mov_b64_e32 v[4:5], 0
	v_mov_b64_e32 v[2:3], 0
	v_mov_b64_e32 v[0:1], 0
	s_cbranch_vccnz .LBB0_1968
	s_and_b64 s[0:1], s[0:1], exec
	s_cselect_b32 s8, s53, s19
	s_cselect_b32 s9, s52, s18
	s_cselect_b32 s22, s55, s3
	s_cselect_b32 s23, s54, s2
	s_add_u32 s49, s2, 0x100
	s_addc_u32 s51, s3, 0
	s_add_u32 s0, s18, 0x20080
	v_mov_b32_e32 v0, 0
	s_addc_u32 s1, s19, 0
	s_mov_b32 s2, 0
	v_mov_b32_e32 v1, v0
	v_mov_b64_e32 v[2:3], 0
	v_mov_b64_e32 v[4:5], 0
	v_mov_b64_e32 v[6:7], 0
	v_mov_b64_e32 v[16:17], 0
	v_mov_b64_e32 v[18:19], 0
	v_mov_b64_e32 v[20:21], 0
	v_mov_b64_e32 v[22:23], 0
	v_mov_b64_e32 v[32:33], 0
	v_mov_b64_e32 v[34:35], 0
	v_mov_b64_e32 v[36:37], 0
	v_mov_b64_e32 v[38:39], 0
	v_mov_b64_e32 v[48:49], 0
	v_mov_b64_e32 v[50:51], 0
	v_mov_b64_e32 v[52:53], 0
	v_mov_b64_e32 v[54:55], 0
	v_mov_b64_e32 v[8:9], 0
	v_mov_b64_e32 v[10:11], 0
	v_mov_b64_e32 v[12:13], 0
	v_mov_b64_e32 v[14:15], 0
	v_mov_b64_e32 v[24:25], 0
	v_mov_b64_e32 v[26:27], 0
	v_mov_b64_e32 v[28:29], 0
	v_mov_b64_e32 v[30:31], 0
	v_mov_b64_e32 v[40:41], 0
	v_mov_b64_e32 v[42:43], 0
	v_mov_b64_e32 v[44:45], 0
	v_mov_b64_e32 v[46:47], 0
	v_mov_b64_e32 v[56:57], 0
	v_mov_b64_e32 v[58:59], 0
	v_mov_b64_e32 v[60:61], 0
	v_mov_b64_e32 v[62:63], 0
	v_mov_b64_e32 v[64:65], 0
	v_mov_b64_e32 v[66:67], 0
	v_mov_b64_e32 v[68:69], 0
	v_mov_b64_e32 v[70:71], 0
	v_mov_b64_e32 v[80:81], 0
	v_mov_b64_e32 v[82:83], 0
	v_mov_b64_e32 v[84:85], 0
	v_mov_b64_e32 v[86:87], 0
	v_mov_b64_e32 v[96:97], 0
	v_mov_b64_e32 v[98:99], 0
	v_mov_b64_e32 v[100:101], 0
	v_mov_b64_e32 v[102:103], 0
	v_mov_b64_e32 v[112:113], 0
	v_mov_b64_e32 v[114:115], 0
	v_mov_b64_e32 v[116:117], 0
	v_mov_b64_e32 v[118:119], 0
	v_mov_b64_e32 v[72:73], 0
	v_mov_b64_e32 v[74:75], 0
	v_mov_b64_e32 v[76:77], 0
	v_mov_b64_e32 v[78:79], 0
	v_mov_b64_e32 v[88:89], 0
	v_mov_b64_e32 v[90:91], 0
	v_mov_b64_e32 v[92:93], 0
	v_mov_b64_e32 v[94:95], 0
	v_mov_b64_e32 v[104:105], 0
	v_mov_b64_e32 v[106:107], 0
	v_mov_b64_e32 v[108:109], 0
	v_mov_b64_e32 v[110:111], 0
	v_mov_b64_e32 v[120:121], 0
	v_mov_b64_e32 v[122:123], 0
	v_mov_b64_e32 v[124:125], 0
	v_mov_b64_e32 v[126:127], 0

.LBB0_2371:
	s_ashr_i32 s51, s50, 31
	s_lshl_b64 s[2:3], s[50:51], 19
	v_readlane_b32 s38, v251, 3
	v_readlane_b32 s39, v251, 4
	s_add_u32 s2, s38, s2
	s_addc_u32 s3, s39, s3
	s_ashr_i32 s49, s48, 31
	s_lshl_b64 s[52:53], s[48:49], 19
	v_readlane_b32 s38, v255, 23
	v_mov_b64_e32 v[0:1], 0x5ac
	v_readlane_b32 s39, v255, 24
	s_add_u32 s52, s38, s52
	v_mov_b32_e32 v127, 0
	v_cmp_lt_i64_e64 s[0:1], s[0:1], v[0:1]
	s_addc_u32 s53, s39, s53
	s_andn2_b64 vcc, exec, s[46:47]
	v_mov_b32_e32 v126, v127
	v_mov_b64_e32 v[124:125], 0
	v_mov_b64_e32 v[122:123], 0
	v_mov_b64_e32 v[120:121], 0
	v_mov_b64_e32 v[110:111], 0
	v_mov_b64_e32 v[108:109], 0
	v_mov_b64_e32 v[106:107], 0
	v_mov_b64_e32 v[104:105], 0
	v_mov_b64_e32 v[94:95], 0
	v_mov_b64_e32 v[92:93], 0
	v_mov_b64_e32 v[90:91], 0
	v_mov_b64_e32 v[88:89], 0
	v_mov_b64_e32 v[78:79], 0
	v_mov_b64_e32 v[76:77], 0
	v_mov_b64_e32 v[74:75], 0
	v_mov_b64_e32 v[72:73], 0
	v_mov_b64_e32 v[118:119], 0
	v_mov_b64_e32 v[116:117], 0
	v_mov_b64_e32 v[114:115], 0
	v_mov_b64_e32 v[112:113], 0
	v_mov_b64_e32 v[102:103], 0
	v_mov_b64_e32 v[100:101], 0
	v_mov_b64_e32 v[98:99], 0
	v_mov_b64_e32 v[96:97], 0
	v_mov_b64_e32 v[86:87], 0
	v_mov_b64_e32 v[84:85], 0
	v_mov_b64_e32 v[82:83], 0
	v_mov_b64_e32 v[80:81], 0
	v_mov_b64_e32 v[70:71], 0
	v_mov_b64_e32 v[68:69], 0
	v_mov_b64_e32 v[66:67], 0
	v_mov_b64_e32 v[64:65], 0
	v_mov_b64_e32 v[62:63], 0
	v_mov_b64_e32 v[60:61], 0
	v_mov_b64_e32 v[58:59], 0
	v_mov_b64_e32 v[56:57], 0
	v_mov_b64_e32 v[46:47], 0
	v_mov_b64_e32 v[44:45], 0
	v_mov_b64_e32 v[42:43], 0
	v_mov_b64_e32 v[40:41], 0
	v_mov_b64_e32 v[30:31], 0
	v_mov_b64_e32 v[28:29], 0
	v_mov_b64_e32 v[26:27], 0
	v_mov_b64_e32 v[24:25], 0
	v_mov_b64_e32 v[14:15], 0
	v_mov_b64_e32 v[12:13], 0
	v_mov_b64_e32 v[10:11], 0
	v_mov_b64_e32 v[8:9], 0
	v_mov_b64_e32 v[54:55], 0
	v_mov_b64_e32 v[52:53], 0
	v_mov_b64_e32 v[50:51], 0
	v_mov_b64_e32 v[48:49], 0
	v_mov_b64_e32 v[38:39], 0
	v_mov_b64_e32 v[36:37], 0
	v_mov_b64_e32 v[34:35], 0
	v_mov_b64_e32 v[32:33], 0
	v_mov_b64_e32 v[22:23], 0
	v_mov_b64_e32 v[20:21], 0
	v_mov_b64_e32 v[18:19], 0
	v_mov_b64_e32 v[16:17], 0
	v_mov_b64_e32 v[6:7], 0
	v_mov_b64_e32 v[4:5], 0
	v_mov_b64_e32 v[2:3], 0
	v_mov_b64_e32 v[0:1], 0
	s_cbranch_vccnz .LBB0_2364
	s_and_b64 s[0:1], s[0:1], exec
	s_cselect_b32 s49, s3, s55
	s_cselect_b32 s51, s2, s54
	s_cselect_b32 s60, s53, s19
	s_cselect_b32 s61, s52, s18
	s_add_u32 s62, s18, 0x100
	s_addc_u32 s63, s19, 0
	s_add_u32 s0, s54, 0x40080
	v_mov_b32_e32 v0, 0
	s_addc_u32 s1, s55, 0
	s_mov_b32 s18, 0
	v_mov_b32_e32 v1, v0
	v_mov_b64_e32 v[2:3], 0
	v_mov_b64_e32 v[4:5], 0
	v_mov_b64_e32 v[6:7], 0
	v_mov_b64_e32 v[16:17], 0
	v_mov_b64_e32 v[18:19], 0
	v_mov_b64_e32 v[20:21], 0
	v_mov_b64_e32 v[22:23], 0
	v_mov_b64_e32 v[32:33], 0
	v_mov_b64_e32 v[34:35], 0
	v_mov_b64_e32 v[36:37], 0
	v_mov_b64_e32 v[38:39], 0
	v_mov_b64_e32 v[48:49], 0
	v_mov_b64_e32 v[50:51], 0
	v_mov_b64_e32 v[52:53], 0
	v_mov_b64_e32 v[54:55], 0
	v_mov_b64_e32 v[8:9], 0
	v_mov_b64_e32 v[10:11], 0
	v_mov_b64_e32 v[12:13], 0
	v_mov_b64_e32 v[14:15], 0
	v_mov_b64_e32 v[24:25], 0
	v_mov_b64_e32 v[26:27], 0
	v_mov_b64_e32 v[28:29], 0
	v_mov_b64_e32 v[30:31], 0
	v_mov_b64_e32 v[40:41], 0
	v_mov_b64_e32 v[42:43], 0
	v_mov_b64_e32 v[44:45], 0
	v_mov_b64_e32 v[46:47], 0
	v_mov_b64_e32 v[56:57], 0
	v_mov_b64_e32 v[58:59], 0
	v_mov_b64_e32 v[60:61], 0
	v_mov_b64_e32 v[62:63], 0
	v_mov_b64_e32 v[64:65], 0
	v_mov_b64_e32 v[66:67], 0
	v_mov_b64_e32 v[68:69], 0
	v_mov_b64_e32 v[70:71], 0
	v_mov_b64_e32 v[80:81], 0
	v_mov_b64_e32 v[82:83], 0
	v_mov_b64_e32 v[84:85], 0
	v_mov_b64_e32 v[86:87], 0
	v_mov_b64_e32 v[96:97], 0
	v_mov_b64_e32 v[98:99], 0
	v_mov_b64_e32 v[100:101], 0
	v_mov_b64_e32 v[102:103], 0
	v_mov_b64_e32 v[112:113], 0
	v_mov_b64_e32 v[114:115], 0
	v_mov_b64_e32 v[116:117], 0
	v_mov_b64_e32 v[118:119], 0
	v_mov_b64_e32 v[72:73], 0
	v_mov_b64_e32 v[74:75], 0
	v_mov_b64_e32 v[76:77], 0
	v_mov_b64_e32 v[78:79], 0
	v_mov_b64_e32 v[88:89], 0
	v_mov_b64_e32 v[90:91], 0
	v_mov_b64_e32 v[92:93], 0
	v_mov_b64_e32 v[94:95], 0
	v_mov_b64_e32 v[104:105], 0
	v_mov_b64_e32 v[106:107], 0
	v_mov_b64_e32 v[108:109], 0
	v_mov_b64_e32 v[110:111], 0
	v_mov_b64_e32 v[120:121], 0
	v_mov_b64_e32 v[122:123], 0
	v_mov_b64_e32 v[124:125], 0
	v_mov_b64_e32 v[126:127], 0

.LBB0_2387:
	s_ashr_i32 s49, s48, 31
	s_lshl_b64 s[2:3], s[48:49], 19
	v_readlane_b32 s38, v251, 3
	v_readlane_b32 s39, v251, 4
	s_add_u32 s2, s38, s2
	s_addc_u32 s3, s39, s3
	s_ashr_i32 s47, s46, 31
	s_lshl_b64 s[50:51], s[46:47], 19
	v_readlane_b32 s38, v255, 23
	v_readlane_b32 s39, v255, 24
	s_add_u32 s50, s38, s50
	v_mov_b32_e32 v127, 0
	s_addc_u32 s51, s39, s51
	s_andn2_b64 vcc, exec, s[0:1]
	v_mov_b32_e32 v126, v127
	v_mov_b64_e32 v[124:125], 0
	v_mov_b64_e32 v[122:123], 0
	v_mov_b64_e32 v[120:121], 0
	v_mov_b64_e32 v[110:111], 0
	v_mov_b64_e32 v[108:109], 0
	v_mov_b64_e32 v[106:107], 0
	v_mov_b64_e32 v[104:105], 0
	v_mov_b64_e32 v[94:95], 0
	v_mov_b64_e32 v[92:93], 0
	v_mov_b64_e32 v[90:91], 0
	v_mov_b64_e32 v[88:89], 0
	v_mov_b64_e32 v[78:79], 0
	v_mov_b64_e32 v[76:77], 0
	v_mov_b64_e32 v[74:75], 0
	v_mov_b64_e32 v[72:73], 0
	v_mov_b64_e32 v[118:119], 0
	v_mov_b64_e32 v[116:117], 0
	v_mov_b64_e32 v[114:115], 0
	v_mov_b64_e32 v[112:113], 0
	v_mov_b64_e32 v[102:103], 0
	v_mov_b64_e32 v[100:101], 0
	v_mov_b64_e32 v[98:99], 0
	v_mov_b64_e32 v[96:97], 0
	v_mov_b64_e32 v[86:87], 0
	v_mov_b64_e32 v[84:85], 0
	v_mov_b64_e32 v[82:83], 0
	v_mov_b64_e32 v[80:81], 0
	v_mov_b64_e32 v[70:71], 0
	v_mov_b64_e32 v[68:69], 0
	v_mov_b64_e32 v[66:67], 0
	v_mov_b64_e32 v[64:65], 0
	v_mov_b64_e32 v[62:63], 0
	v_mov_b64_e32 v[60:61], 0
	v_mov_b64_e32 v[58:59], 0
	v_mov_b64_e32 v[56:57], 0
	v_mov_b64_e32 v[46:47], 0
	v_mov_b64_e32 v[44:45], 0
	v_mov_b64_e32 v[42:43], 0
	v_mov_b64_e32 v[40:41], 0
	v_mov_b64_e32 v[30:31], 0
	v_mov_b64_e32 v[28:29], 0
	v_mov_b64_e32 v[26:27], 0
	v_mov_b64_e32 v[24:25], 0
	v_mov_b64_e32 v[14:15], 0
	v_mov_b64_e32 v[12:13], 0
	v_mov_b64_e32 v[10:11], 0
	v_mov_b64_e32 v[8:9], 0
	v_mov_b64_e32 v[54:55], 0
	v_mov_b64_e32 v[52:53], 0
	v_mov_b64_e32 v[50:51], 0
	v_mov_b64_e32 v[48:49], 0
	v_mov_b64_e32 v[38:39], 0
	v_mov_b64_e32 v[36:37], 0
	v_mov_b64_e32 v[34:35], 0
	v_mov_b64_e32 v[32:33], 0
	v_mov_b64_e32 v[22:23], 0
	v_mov_b64_e32 v[20:21], 0
	v_mov_b64_e32 v[18:19], 0
	v_mov_b64_e32 v[16:17], 0
	v_mov_b64_e32 v[6:7], 0
	v_mov_b64_e32 v[4:5], 0
	v_mov_b64_e32 v[2:3], 0
	v_mov_b64_e32 v[0:1], 0
	s_cbranch_vccnz .LBB0_2384
	v_mov_b64_e32 v[0:1], 0x580
	v_cmp_lt_i64_e32 vcc, s[54:55], v[0:1]
	s_and_b64 s[54:55], vcc, exec
	s_cselect_b32 s47, s3, s53
	s_cselect_b32 s49, s2, s52
	s_cselect_b32 s60, s51, s19
	s_cselect_b32 s61, s50, s18
	s_add_u32 s62, s18, 0x100
	s_addc_u32 s63, s19, 0
	s_add_u32 s18, s52, 0x40080
	v_mov_b32_e32 v0, 0
	s_addc_u32 s19, s53, 0
	s_mov_b32 s52, 0
	v_mov_b32_e32 v1, v0
	v_mov_b64_e32 v[2:3], 0
	v_mov_b64_e32 v[4:5], 0
	v_mov_b64_e32 v[6:7], 0
	v_mov_b64_e32 v[16:17], 0
	v_mov_b64_e32 v[18:19], 0
	v_mov_b64_e32 v[20:21], 0
	v_mov_b64_e32 v[22:23], 0
	v_mov_b64_e32 v[32:33], 0
	v_mov_b64_e32 v[34:35], 0
	v_mov_b64_e32 v[36:37], 0
	v_mov_b64_e32 v[38:39], 0
	v_mov_b64_e32 v[48:49], 0
	v_mov_b64_e32 v[50:51], 0
	v_mov_b64_e32 v[52:53], 0
	v_mov_b64_e32 v[54:55], 0
	v_mov_b64_e32 v[8:9], 0
	v_mov_b64_e32 v[10:11], 0
	v_mov_b64_e32 v[12:13], 0
	v_mov_b64_e32 v[14:15], 0
	v_mov_b64_e32 v[24:25], 0
	v_mov_b64_e32 v[26:27], 0
	v_mov_b64_e32 v[28:29], 0
	v_mov_b64_e32 v[30:31], 0
	v_mov_b64_e32 v[40:41], 0
	v_mov_b64_e32 v[42:43], 0
	v_mov_b64_e32 v[44:45], 0
	v_mov_b64_e32 v[46:47], 0
	v_mov_b64_e32 v[56:57], 0
	v_mov_b64_e32 v[58:59], 0
	v_mov_b64_e32 v[60:61], 0
	v_mov_b64_e32 v[62:63], 0
	v_mov_b64_e32 v[64:65], 0
	v_mov_b64_e32 v[66:67], 0
	v_mov_b64_e32 v[68:69], 0
	v_mov_b64_e32 v[70:71], 0
	v_mov_b64_e32 v[80:81], 0
	v_mov_b64_e32 v[82:83], 0
	v_mov_b64_e32 v[84:85], 0
	v_mov_b64_e32 v[86:87], 0
	v_mov_b64_e32 v[96:97], 0
	v_mov_b64_e32 v[98:99], 0
	v_mov_b64_e32 v[100:101], 0
	v_mov_b64_e32 v[102:103], 0
	v_mov_b64_e32 v[112:113], 0
	v_mov_b64_e32 v[114:115], 0
	v_mov_b64_e32 v[116:117], 0
	v_mov_b64_e32 v[118:119], 0
	v_mov_b64_e32 v[72:73], 0
	v_mov_b64_e32 v[74:75], 0
	v_mov_b64_e32 v[76:77], 0
	v_mov_b64_e32 v[78:79], 0
	v_mov_b64_e32 v[88:89], 0
	v_mov_b64_e32 v[90:91], 0
	v_mov_b64_e32 v[92:93], 0
	v_mov_b64_e32 v[94:95], 0
	v_mov_b64_e32 v[104:105], 0
	v_mov_b64_e32 v[106:107], 0
	v_mov_b64_e32 v[108:109], 0
	v_mov_b64_e32 v[110:111], 0
	v_mov_b64_e32 v[120:121], 0
	v_mov_b64_e32 v[122:123], 0
	v_mov_b64_e32 v[124:125], 0
	v_mov_b64_e32 v[126:127], 0

.LBB0_2465:
	s_add_i32 s60, s59, -2
	s_add_u32 s61, s44, 0x100
	v_mov_b32_e32 v0, 0
	s_addc_u32 s62, s45, 0
	s_mov_b32 s46, 0
	v_mov_b32_e32 v1, v0
	v_mov_b64_e32 v[2:3], 0
	v_mov_b64_e32 v[4:5], 0
	v_mov_b64_e32 v[6:7], 0
	v_mov_b64_e32 v[16:17], 0
	v_mov_b64_e32 v[18:19], 0
	v_mov_b64_e32 v[20:21], 0
	v_mov_b64_e32 v[22:23], 0
	v_mov_b64_e32 v[32:33], 0
	v_mov_b64_e32 v[34:35], 0
	v_mov_b64_e32 v[36:37], 0
	v_mov_b64_e32 v[38:39], 0
	v_mov_b64_e32 v[48:49], 0
	v_mov_b64_e32 v[50:51], 0
	v_mov_b64_e32 v[52:53], 0
	v_mov_b64_e32 v[54:55], 0
	v_mov_b64_e32 v[8:9], 0
	v_mov_b64_e32 v[10:11], 0
	v_mov_b64_e32 v[12:13], 0
	v_mov_b64_e32 v[14:15], 0
	v_mov_b64_e32 v[24:25], 0
	v_mov_b64_e32 v[26:27], 0
	v_mov_b64_e32 v[28:29], 0
	v_mov_b64_e32 v[30:31], 0
	v_mov_b64_e32 v[40:41], 0
	v_mov_b64_e32 v[42:43], 0
	v_mov_b64_e32 v[44:45], 0
	v_mov_b64_e32 v[46:47], 0
	v_mov_b64_e32 v[56:57], 0
	v_mov_b64_e32 v[58:59], 0
	v_mov_b64_e32 v[60:61], 0
	v_mov_b64_e32 v[62:63], 0
	v_mov_b64_e32 v[64:65], 0
	v_mov_b64_e32 v[66:67], 0
	v_mov_b64_e32 v[68:69], 0
	v_mov_b64_e32 v[70:71], 0
	v_mov_b64_e32 v[80:81], 0
	v_mov_b64_e32 v[82:83], 0
	v_mov_b64_e32 v[84:85], 0
	v_mov_b64_e32 v[86:87], 0
	v_mov_b64_e32 v[96:97], 0
	v_mov_b64_e32 v[98:99], 0
	v_mov_b64_e32 v[100:101], 0
	v_mov_b64_e32 v[102:103], 0
	v_mov_b64_e32 v[130:131], 0
	v_mov_b64_e32 v[132:133], 0
	v_mov_b64_e32 v[134:135], 0
	v_mov_b64_e32 v[136:137], 0
	v_mov_b64_e32 v[72:73], 0
	v_mov_b64_e32 v[74:75], 0
	v_mov_b64_e32 v[76:77], 0
	v_mov_b64_e32 v[78:79], 0
	v_mov_b64_e32 v[88:89], 0
	v_mov_b64_e32 v[90:91], 0
	v_mov_b64_e32 v[92:93], 0
	v_mov_b64_e32 v[94:95], 0
	v_mov_b64_e32 v[104:105], 0
	v_mov_b64_e32 v[106:107], 0
	v_mov_b64_e32 v[108:109], 0
	v_mov_b64_e32 v[110:111], 0
	v_mov_b64_e32 v[138:139], 0
	v_mov_b64_e32 v[140:141], 0
	v_mov_b64_e32 v[142:143], 0
	v_mov_b64_e32 v[144:145], 0

.LBB0_2557:
	v_mov_b32_e32 v127, 0
	s_andn2_b64 vcc, exec, s[2:3]
	v_mov_b32_e32 v126, v127
	v_mov_b64_e32 v[124:125], 0
	v_mov_b64_e32 v[122:123], 0
	v_mov_b64_e32 v[120:121], 0
	v_mov_b64_e32 v[110:111], 0
	v_mov_b64_e32 v[108:109], 0
	v_mov_b64_e32 v[106:107], 0
	v_mov_b64_e32 v[104:105], 0
	v_mov_b64_e32 v[94:95], 0
	v_mov_b64_e32 v[92:93], 0
	v_mov_b64_e32 v[90:91], 0
	v_mov_b64_e32 v[88:89], 0
	v_mov_b64_e32 v[78:79], 0
	v_mov_b64_e32 v[76:77], 0
	v_mov_b64_e32 v[74:75], 0
	v_mov_b64_e32 v[72:73], 0
	v_mov_b64_e32 v[118:119], 0
	v_mov_b64_e32 v[116:117], 0
	v_mov_b64_e32 v[114:115], 0
	v_mov_b64_e32 v[112:113], 0
	v_mov_b64_e32 v[102:103], 0
	v_mov_b64_e32 v[100:101], 0
	v_mov_b64_e32 v[98:99], 0
	v_mov_b64_e32 v[96:97], 0
	v_mov_b64_e32 v[86:87], 0
	v_mov_b64_e32 v[84:85], 0
	v_mov_b64_e32 v[82:83], 0
	v_mov_b64_e32 v[80:81], 0
	v_mov_b64_e32 v[70:71], 0
	v_mov_b64_e32 v[68:69], 0
	v_mov_b64_e32 v[66:67], 0
	v_mov_b64_e32 v[64:65], 0
	v_mov_b64_e32 v[62:63], 0
	v_mov_b64_e32 v[60:61], 0
	v_mov_b64_e32 v[58:59], 0
	v_mov_b64_e32 v[56:57], 0
	v_mov_b64_e32 v[46:47], 0
	v_mov_b64_e32 v[44:45], 0
	v_mov_b64_e32 v[42:43], 0
	v_mov_b64_e32 v[40:41], 0
	v_mov_b64_e32 v[30:31], 0
	v_mov_b64_e32 v[28:29], 0
	v_mov_b64_e32 v[26:27], 0
	v_mov_b64_e32 v[24:25], 0
	v_mov_b64_e32 v[14:15], 0
	v_mov_b64_e32 v[12:13], 0
	v_mov_b64_e32 v[10:11], 0
	v_mov_b64_e32 v[8:9], 0
	v_mov_b64_e32 v[54:55], 0
	v_mov_b64_e32 v[52:53], 0
	v_mov_b64_e32 v[50:51], 0
	v_mov_b64_e32 v[48:49], 0
	v_mov_b64_e32 v[38:39], 0
	v_mov_b64_e32 v[36:37], 0
	v_mov_b64_e32 v[34:35], 0
	v_mov_b64_e32 v[32:33], 0
	v_mov_b64_e32 v[22:23], 0
	v_mov_b64_e32 v[20:21], 0
	v_mov_b64_e32 v[18:19], 0
	v_mov_b64_e32 v[16:17], 0
	v_mov_b64_e32 v[6:7], 0
	v_mov_b64_e32 v[4:5], 0
	v_mov_b64_e32 v[2:3], 0
	v_mov_b64_e32 v[0:1], 0
	s_cbranch_vccnz .LBB0_2561
	s_add_u32 s8, s48, 0x100
	v_mov_b32_e32 v0, 0
	s_addc_u32 s9, s49, 0
	s_mov_b32 s48, 0
	v_mov_b32_e32 v1, v0
	v_mov_b64_e32 v[2:3], 0
	v_mov_b64_e32 v[4:5], 0
	v_mov_b64_e32 v[6:7], 0
	v_mov_b64_e32 v[16:17], 0
	v_mov_b64_e32 v[18:19], 0
	v_mov_b64_e32 v[20:21], 0
	v_mov_b64_e32 v[22:23], 0
	v_mov_b64_e32 v[32:33], 0
	v_mov_b64_e32 v[34:35], 0
	v_mov_b64_e32 v[36:37], 0
	v_mov_b64_e32 v[38:39], 0
	v_mov_b64_e32 v[48:49], 0
	v_mov_b64_e32 v[50:51], 0
	v_mov_b64_e32 v[52:53], 0
	v_mov_b64_e32 v[54:55], 0
	v_mov_b64_e32 v[8:9], 0
	v_mov_b64_e32 v[10:11], 0
	v_mov_b64_e32 v[12:13], 0
	v_mov_b64_e32 v[14:15], 0
	v_mov_b64_e32 v[24:25], 0
	v_mov_b64_e32 v[26:27], 0
	v_mov_b64_e32 v[28:29], 0
	v_mov_b64_e32 v[30:31], 0
	v_mov_b64_e32 v[40:41], 0
	v_mov_b64_e32 v[42:43], 0
	v_mov_b64_e32 v[44:45], 0
	v_mov_b64_e32 v[46:47], 0
	v_mov_b64_e32 v[56:57], 0
	v_mov_b64_e32 v[58:59], 0
	v_mov_b64_e32 v[60:61], 0
	v_mov_b64_e32 v[62:63], 0
	v_mov_b64_e32 v[64:65], 0
	v_mov_b64_e32 v[66:67], 0
	v_mov_b64_e32 v[68:69], 0
	v_mov_b64_e32 v[70:71], 0
	v_mov_b64_e32 v[80:81], 0
	v_mov_b64_e32 v[82:83], 0
	v_mov_b64_e32 v[84:85], 0
	v_mov_b64_e32 v[86:87], 0
	v_mov_b64_e32 v[96:97], 0
	v_mov_b64_e32 v[98:99], 0
	v_mov_b64_e32 v[100:101], 0
	v_mov_b64_e32 v[102:103], 0
	v_mov_b64_e32 v[112:113], 0
	v_mov_b64_e32 v[114:115], 0
	v_mov_b64_e32 v[116:117], 0
	v_mov_b64_e32 v[118:119], 0
	v_mov_b64_e32 v[72:73], 0
	v_mov_b64_e32 v[74:75], 0
	v_mov_b64_e32 v[76:77], 0
	v_mov_b64_e32 v[78:79], 0
	v_mov_b64_e32 v[88:89], 0
	v_mov_b64_e32 v[90:91], 0
	v_mov_b64_e32 v[92:93], 0
	v_mov_b64_e32 v[94:95], 0
	v_mov_b64_e32 v[104:105], 0
	v_mov_b64_e32 v[106:107], 0
	v_mov_b64_e32 v[108:109], 0
	v_mov_b64_e32 v[110:111], 0
	v_mov_b64_e32 v[120:121], 0
	v_mov_b64_e32 v[122:123], 0
	v_mov_b64_e32 v[124:125], 0
	v_mov_b64_e32 v[126:127], 0
